# LRU stores: bf16 rounding via v_cvt_pk_bf16_f32 + global_store_short instead of bfe/add3 bit trick (-16 VALU per chunk)
# speedup vs baseline: 1.0076x; 1.0076x over previous
; __device__ __forceinline__ bf16_t f2bf(float f) { unsigned u = __float_as_uint(f); u += 0x7FFFu + ((u >> 16) & 1u); return (bf16_t)(u >> 16); }
; __device__ __forceinline__ float bf2f(bf16_t b) { return __uint_as_float(((unsigned)b) << 16); }
; __device__ void lru_fused_phase(const int bid, const int nblk, bf16_t* __restrict__ U, bf16_t* __restrict__ HF, const bf16_t* __restrict__ Wg, const float* __restrict__ cw, const float* __restrict__ cb, ...
;     ...
; #pragma unroll
;                     for (int j = 0; j < 4; ++j) {
;                         const float hv = hl[j] + pp[j] * carry;
;                         if (e == 0) HF[(grow + j) * DRNN + ch] = f2bf(hv);
;                         else U[(grow + j) * (2 * DRNN) + ch] = f2bf((bf2f(hfv[j]) + hv) * bf2f(gtv[j]));
;                     }
.LBB0_134:
	v_fmac_f32_e32 v40, v36, v37
	s_waitcnt vmcnt(7)
	v_lshlrev_b32_e32 v36, 16, v77
	v_add_f32_e32 v36, v40, v36
	s_waitcnt vmcnt(4) lgkmcnt(0)
	v_lshlrev_b32_e32 v38, 16, v78
	v_mul_f32_e32 v36, v36, v38
	v_cndmask_b32_e64 v36, v36, v40, s[60:61]
	v_lshl_add_u64 v[40:41], v[58:59], 1, s[14:15]
	v_mad_u64_u32 v[40:41], s[14:15], s8, v107, v[40:41]
	v_cvt_pk_bf16_f32 v36, v36, v36
	v_mad_i32_i24 v41, s8, v69, v41
	global_store_short v[40:41], v36, off
	v_fmac_f32_e32 v111, v110, v37
	v_lshlrev_b32_e32 v36, 16, v79
	v_add_f32_e32 v36, v111, v36
	s_waitcnt vmcnt(4)
	v_lshlrev_b32_e32 v38, 16, v80
	v_mul_f32_e32 v36, v36, v38
	v_cndmask_b32_e64 v36, v36, v111, s[60:61]
	v_cvt_pk_bf16_f32 v36, v36, v36
	v_lshl_add_u64 v[40:41], v[40:41], 0, s[8:9]
	global_store_short v[40:41], v36, off
	v_cndmask_b32_e64 v36, 0, 1, s[64:65]
	v_fmac_f32_e32 v108, v109, v37
	v_cmp_ne_u32_e64 s[8:9], 1, v36
	s_andn2_b64 vcc, exec, s[64:65]
	s_mov_b64 s[14:15], 0xa00
	s_cbranch_vccnz .LBB0_136
	v_lshlrev_b32_e32 v36, 16, v81
	v_add_f32_e32 v36, v108, v36
	s_waitcnt vmcnt(4)
	v_lshlrev_b32_e32 v38, 16, v85
	v_mul_f32_e32 v108, v36, v38
	s_mov_b64 s[2:3], 0x2800
	s_mov_b64 s[36:37], 0x1400
	s_mov_b64 s[38:39], s[46:47]
	s_branch .LBB0_137

; __device__ __forceinline__ bf16_t f2bf(float f) { unsigned u = __float_as_uint(f); u += 0x7FFFu + ((u >> 16) & 1u); return (bf16_t)(u >> 16); }
; __device__ __forceinline__ float bf2f(bf16_t b) { return __uint_as_float(((unsigned)b) << 16); }
; __device__ void lru_fused_phase(const int bid, const int nblk, bf16_t* __restrict__ U, bf16_t* __restrict__ HF, const bf16_t* __restrict__ Wg, const float* __restrict__ cw, const float* __restrict__ cb, ...
;     ...
; #pragma unroll
;                     for (int j = 0; j < 4; ++j) {
;                         const float hv = hl[j] + pp[j] * carry;
;                         if (e == 0) HF[(grow + j) * DRNN + ch] = f2bf(hv);
;                         else U[(grow + j) * (2 * DRNN) + ch] = f2bf((bf2f(hfv[j]) + hv) * bf2f(gtv[j]));
;                     }
.LBB0_137:
	v_lshl_add_u64 v[40:41], v[58:59], 1, s[38:39]
	v_mad_u64_u32 v[40:41], s[38:39], s36, v107, v[40:41]
	v_mad_i32_i24 v41, s36, v69, v41
	v_cvt_pk_bf16_f32 v36, v108, v108
	v_lshl_add_u64 v[40:41], v[40:41], 0, s[2:3]
	s_and_b64 vcc, exec, s[8:9]
	v_fmac_f32_e32 v43, v39, v37
	global_store_short v[40:41], v36, off
	s_cbranch_vccnz .LBB0_139
	s_waitcnt vmcnt(4)
	v_lshlrev_b32_e32 v36, 16, v84
	v_add_f32_e32 v36, v43, v36
	s_waitcnt vmcnt(3)
	v_lshlrev_b32_e32 v37, 16, v91
	v_mul_f32_e32 v43, v36, v37
	s_mov_b32 s38, 32
	s_mov_b64 s[2:3], 0x3c00
	s_mov_b64 s[14:15], 0x1400
	s_mov_b64 s[36:37], s[46:47]
	s_branch .LBB0_140

; __device__ __forceinline__ bf16_t f2bf(float f) { unsigned u = __float_as_uint(f); u += 0x7FFFu + ((u >> 16) & 1u); return (bf16_t)(u >> 16); }
; __device__ __forceinline__ float bf2f(bf16_t b) { return __uint_as_float(((unsigned)b) << 16); }
; __device__ void lru_fused_phase(const int bid, const int nblk, bf16_t* __restrict__ U, bf16_t* __restrict__ HF, const bf16_t* __restrict__ Wg, const float* __restrict__ cw, const float* __restrict__ cb, ...
;     ...
;                     const long grow = rowb + 64 * k + 16 * rt + 4 * fq;
;                     unsigned short hfv[4], gtv[4];
;                     if (e == 1) {
; #pragma unroll
;                         for (int j = 0; j < 4; ++j) { hfv[j] = HF[(grow + j) * DRNN + ch]; gtv[j] = U[(grow + j) * (2 * DRNN) + ch]; }
;                     }
;     ...
; #pragma unroll
;                     for (int j = 0; j < 4; ++j) {
;                         const float hv = hl[j] + pp[j] * carry;
;                         if (e == 0) HF[(grow + j) * DRNN + ch] = f2bf(hv);
;                         else U[(grow + j) * (2 * DRNN) + ch] = f2bf((bf2f(hfv[j]) + hv) * bf2f(gtv[j]));
;                     }
.LBB0_140:
	v_lshl_add_u64 v[36:37], v[58:59], 1, s[36:37]
	v_mad_u64_u32 v[36:37], s[36:37], s14, v107, v[36:37]
	v_mad_i32_i24 v37, s14, v69, v37
	v_cvt_pk_bf16_f32 v38, v43, v43
	v_lshl_add_u64 v[36:37], v[36:37], 0, s[2:3]
	s_and_b64 vcc, exec, s[10:11]
	v_or_b32_e32 v107, s38, v68
	global_store_short v[36:37], v38, off
	s_cbranch_vccnz .LBB0_142
	v_mad_u64_u32 v[36:37], s[2:3], v107, s77, v[66:67]
	v_mov_b32_e32 v38, v37
	v_mad_u64_u32 v[38:39], s[2:3], v69, s77, v[38:39]
	v_mov_b32_e32 v37, v38
	v_mad_u64_u32 v[38:39], s[2:3], v107, s43, v[64:65]
	v_mov_b32_e32 v40, v39
	v_lshl_add_u64 v[42:43], v[36:37], 0, s[50:51]
	global_load_ushort v77, v[36:37], off
	global_load_ushort v79, v[36:37], off offset:2560
	global_load_ushort v81, v[42:43], off offset:2560
	v_mad_u64_u32 v[40:41], s[2:3], v69, s43, v[40:41]
	v_add_co_u32_e32 v36, vcc, s33, v38
	v_mov_b32_e32 v39, v40
	s_nop 0
	v_addc_co_u32_e32 v37, vcc, 0, v40, vcc
	global_load_ushort v78, v[38:39], off
	global_load_ushort v80, v[36:37], off offset:1024
	v_lshl_add_u64 v[36:37], v[42:43], 0, s[50:51]
	v_add_co_u32_e32 v42, vcc, 0x2000, v38
	s_nop 1
	v_addc_co_u32_e32 v43, vcc, 0, v40, vcc
	global_load_ushort v85, v[42:43], off offset:2048
	global_load_ushort v84, v[36:37], off offset:2560
	v_add_co_u32_e32 v36, vcc, 0x3000, v38
	s_nop 1
	v_addc_co_u32_e32 v37, vcc, 0, v40, vcc
	global_load_ushort v91, v[36:37], off offset:3072

; __device__ __forceinline__ bf16_t f2bf(float f) { unsigned u = __float_as_uint(f); u += 0x7FFFu + ((u >> 16) & 1u); return (bf16_t)(u >> 16); }
; __device__ __forceinline__ float bf2f(bf16_t b) { return __uint_as_float(((unsigned)b) << 16); }
; __device__ void lru_fused_phase(const int bid, const int nblk, bf16_t* __restrict__ U, bf16_t* __restrict__ HF, const bf16_t* __restrict__ Wg, const float* __restrict__ cw, const float* __restrict__ cb, ...
;     ...
; #pragma unroll
;                     for (int j = 0; j < 4; ++j) {
;                         const float hv = hl[j] + pp[j] * carry;
;                         if (e == 0) HF[(grow + j) * DRNN + ch] = f2bf(hv);
;                         else U[(grow + j) * (2 * DRNN) + ch] = f2bf((bf2f(hfv[j]) + hv) * bf2f(gtv[j]));
;                     }
.LBB0_157:
	v_fmac_f32_e32 v40, v36, v37
	s_waitcnt vmcnt(7)
	v_lshlrev_b32_e32 v36, 16, v77
	v_add_f32_e32 v36, v40, v36
	s_waitcnt vmcnt(4) lgkmcnt(0)
	v_lshlrev_b32_e32 v38, 16, v78
	v_mul_f32_e32 v36, v36, v38
	v_cndmask_b32_e64 v36, v36, v40, s[60:61]
	v_lshl_add_u64 v[40:41], v[58:59], 1, s[36:37]
	v_mad_u64_u32 v[40:41], s[36:37], s14, v107, v[40:41]
	v_cvt_pk_bf16_f32 v38, v36, v36
	v_mov_b32_e32 v36, v41
	v_mad_u64_u32 v[112:113], s[36:37], s14, v69, v[36:37]
	v_mov_b32_e32 v41, v112
	v_fmac_f32_e32 v111, v110, v37
	v_lshlrev_b32_e32 v36, 16, v79
	global_store_short v[40:41], v38, off
	v_add_f32_e32 v36, v111, v36
	s_waitcnt vmcnt(4)
	v_lshlrev_b32_e32 v38, 16, v80
	v_mul_f32_e32 v36, v36, v38
	v_cndmask_b32_e64 v36, v36, v111, s[60:61]
	v_cvt_pk_bf16_f32 v36, v36, v36
	v_lshl_add_u64 v[40:41], v[40:41], 0, s[14:15]
	v_fmac_f32_e32 v108, v109, v37
	s_and_b64 vcc, exec, s[8:9]
	s_mov_b64 s[14:15], 0xa00
	global_store_short v[40:41], v36, off
	s_cbranch_vccnz .LBB0_159
	v_lshlrev_b32_e32 v36, 16, v81
	v_add_f32_e32 v36, v108, v36
	s_waitcnt vmcnt(4)
	v_lshlrev_b32_e32 v38, 16, v85
	v_mul_f32_e32 v108, v36, v38
	s_mov_b64 s[2:3], 0x2800
	s_mov_b64 s[36:37], 0x1400
	s_mov_b64 s[38:39], s[46:47]
	s_branch .LBB0_160

; __device__ __forceinline__ bf16_t f2bf(float f) { unsigned u = __float_as_uint(f); u += 0x7FFFu + ((u >> 16) & 1u); return (bf16_t)(u >> 16); }
; __device__ __forceinline__ float bf2f(bf16_t b) { return __uint_as_float(((unsigned)b) << 16); }
; __device__ void lru_fused_phase(const int bid, const int nblk, bf16_t* __restrict__ U, bf16_t* __restrict__ HF, const bf16_t* __restrict__ Wg, const float* __restrict__ cw, const float* __restrict__ cb, ...
;     ...
; #pragma unroll
;                     for (int j = 0; j < 4; ++j) {
;                         const float hv = hl[j] + pp[j] * carry;
;                         if (e == 0) HF[(grow + j) * DRNN + ch] = f2bf(hv);
;                         else U[(grow + j) * (2 * DRNN) + ch] = f2bf((bf2f(hfv[j]) + hv) * bf2f(gtv[j]));
;                     }
.LBB0_160:
	v_lshl_add_u64 v[40:41], v[58:59], 1, s[38:39]
	v_mad_u64_u32 v[40:41], s[38:39], s36, v107, v[40:41]
	v_cvt_pk_bf16_f32 v38, v108, v108
	v_mov_b32_e32 v36, v41
	v_mad_u64_u32 v[108:109], s[36:37], s36, v69, v[36:37]
	v_mov_b32_e32 v41, v108
	v_lshl_add_u64 v[40:41], v[40:41], 0, s[2:3]
	s_and_b64 vcc, exec, s[8:9]
	v_fmac_f32_e32 v43, v39, v37
	global_store_short v[40:41], v38, off
	s_cbranch_vccnz .LBB0_162
	s_waitcnt vmcnt(4)
	v_lshlrev_b32_e32 v36, 16, v84
	v_add_f32_e32 v36, v43, v36
	s_waitcnt vmcnt(3)
	v_lshlrev_b32_e32 v37, 16, v91
	v_mul_f32_e32 v43, v36, v37
	s_mov_b32 s38, 16
	s_mov_b64 s[2:3], 0x3c00
	s_mov_b64 s[14:15], 0x1400
	s_mov_b64 s[36:37], s[46:47]
	s_branch .LBB0_163

; __device__ __forceinline__ bf16_t f2bf(float f) { unsigned u = __float_as_uint(f); u += 0x7FFFu + ((u >> 16) & 1u); return (bf16_t)(u >> 16); }
; __device__ __forceinline__ float bf2f(bf16_t b) { return __uint_as_float(((unsigned)b) << 16); }
; __device__ void lru_fused_phase(const int bid, const int nblk, bf16_t* __restrict__ U, bf16_t* __restrict__ HF, const bf16_t* __restrict__ Wg, const float* __restrict__ cw, const float* __restrict__ cb, ...
;     ...
;                     const long grow = rowb + 64 * k + 16 * rt + 4 * fq;
;                     unsigned short hfv[4], gtv[4];
;                     if (e == 1) {
; #pragma unroll
;                         for (int j = 0; j < 4; ++j) { hfv[j] = HF[(grow + j) * DRNN + ch]; gtv[j] = U[(grow + j) * (2 * DRNN) + ch]; }
;                     }
;     ...
; #pragma unroll
;                     for (int j = 0; j < 4; ++j) {
;                         const float hv = hl[j] + pp[j] * carry;
;                         if (e == 0) HF[(grow + j) * DRNN + ch] = f2bf(hv);
;                         else U[(grow + j) * (2 * DRNN) + ch] = f2bf((bf2f(hfv[j]) + hv) * bf2f(gtv[j]));
;                     }
.LBB0_163:
	v_lshl_add_u64 v[36:37], v[58:59], 1, s[36:37]
	v_mad_u64_u32 v[36:37], s[36:37], s14, v107, v[36:37]
	v_cvt_pk_bf16_f32 v40, v43, v43
	v_mov_b32_e32 v38, v37
	v_mad_u64_u32 v[38:39], s[14:15], s14, v69, v[38:39]
	v_mov_b32_e32 v37, v38
	v_lshl_add_u64 v[36:37], v[36:37], 0, s[2:3]
	s_and_b64 vcc, exec, s[10:11]
	v_or_b32_e32 v107, s38, v68
	global_store_short v[36:37], v40, off
	s_cbranch_vccnz .LBB0_165
	v_mad_u64_u32 v[36:37], s[2:3], v107, s77, v[66:67]
	v_mov_b32_e32 v38, v37
	v_mad_u64_u32 v[38:39], s[2:3], v69, s77, v[38:39]
	v_mov_b32_e32 v37, v38
	v_mad_u64_u32 v[38:39], s[2:3], v107, s43, v[64:65]
	v_mov_b32_e32 v40, v39
	v_lshl_add_u64 v[42:43], v[36:37], 0, s[50:51]
	global_load_ushort v77, v[36:37], off
	global_load_ushort v79, v[36:37], off offset:2560
	global_load_ushort v81, v[42:43], off offset:2560
	v_mad_u64_u32 v[40:41], s[2:3], v69, s43, v[40:41]
	v_add_co_u32_e32 v36, vcc, s33, v38
	v_mov_b32_e32 v39, v40
	s_nop 0
	v_addc_co_u32_e32 v37, vcc, 0, v40, vcc
	global_load_ushort v78, v[38:39], off
	global_load_ushort v80, v[36:37], off offset:1024
	v_lshl_add_u64 v[36:37], v[42:43], 0, s[50:51]
	v_add_co_u32_e32 v42, vcc, 0x2000, v38
	s_nop 1
	v_addc_co_u32_e32 v43, vcc, 0, v40, vcc
	global_load_ushort v85, v[42:43], off offset:2048
	global_load_ushort v84, v[36:37], off offset:2560
	v_add_co_u32_e32 v36, vcc, 0x3000, v38
	s_nop 1
	v_addc_co_u32_e32 v37, vcc, 0, v40, vcc
	global_load_ushort v91, v[36:37], off offset:3072

; __device__ __forceinline__ bf16_t f2bf(float f) { unsigned u = __float_as_uint(f); u += 0x7FFFu + ((u >> 16) & 1u); return (bf16_t)(u >> 16); }
; __device__ __forceinline__ float bf2f(bf16_t b) { return __uint_as_float(((unsigned)b) << 16); }
; __device__ void lru_fused_phase(const int bid, const int nblk, bf16_t* __restrict__ U, bf16_t* __restrict__ HF, const bf16_t* __restrict__ Wg, const float* __restrict__ cw, const float* __restrict__ cb, ...
;     ...
; #pragma unroll
;                     for (int j = 0; j < 4; ++j) {
;                         const float hv = hl[j] + pp[j] * carry;
;                         if (e == 0) HF[(grow + j) * DRNN + ch] = f2bf(hv);
;                         else U[(grow + j) * (2 * DRNN) + ch] = f2bf((bf2f(hfv[j]) + hv) * bf2f(gtv[j]));
;                     }
.LBB0_183:
	v_lshl_add_u64 v[40:41], v[58:59], 1, s[38:39]
	v_mad_u64_u32 v[40:41], s[38:39], s36, v107, v[40:41]
	v_cvt_pk_bf16_f32 v38, v108, v108
	v_mov_b32_e32 v36, v41
	v_mad_u64_u32 v[108:109], s[36:37], s36, v69, v[36:37]
	v_mov_b32_e32 v41, v108
	v_lshl_add_u64 v[40:41], v[40:41], 0, s[2:3]
	s_and_b64 vcc, exec, s[8:9]
	v_fmac_f32_e32 v43, v39, v37
	global_store_short v[40:41], v38, off
	s_cbranch_vccnz .LBB0_185
	s_waitcnt vmcnt(4)
	v_lshlrev_b32_e32 v36, 16, v84
	v_add_f32_e32 v36, v43, v36
	s_waitcnt vmcnt(3)
	v_lshlrev_b32_e32 v37, 16, v91
	v_mul_f32_e32 v43, v36, v37
	s_mov_b32 s38, 0
	s_mov_b64 s[2:3], 0x3c00
	s_mov_b64 s[14:15], 0x1400
	s_mov_b64 s[36:37], s[46:47]
	s_branch .LBB0_186

; __device__ __forceinline__ bf16_t f2bf(float f) { unsigned u = __float_as_uint(f); u += 0x7FFFu + ((u >> 16) & 1u); return (bf16_t)(u >> 16); }
; __device__ __forceinline__ float bf2f(bf16_t b) { return __uint_as_float(((unsigned)b) << 16); }
; __device__ void lru_fused_phase(const int bid, const int nblk, bf16_t* __restrict__ U, bf16_t* __restrict__ HF, const bf16_t* __restrict__ Wg, const float* __restrict__ cw, const float* __restrict__ cb, ...
;     ...
;                     const long grow = rowb + 64 * k + 16 * rt + 4 * fq;
;                     unsigned short hfv[4], gtv[4];
;                     if (e == 1) {
; #pragma unroll
;                         for (int j = 0; j < 4; ++j) { hfv[j] = HF[(grow + j) * DRNN + ch]; gtv[j] = U[(grow + j) * (2 * DRNN) + ch]; }
;                     }
;     ...
; #pragma unroll
;                     for (int j = 0; j < 4; ++j) {
;                         const float hv = hl[j] + pp[j] * carry;
;                         if (e == 0) HF[(grow + j) * DRNN + ch] = f2bf(hv);
;                         else U[(grow + j) * (2 * DRNN) + ch] = f2bf((bf2f(hfv[j]) + hv) * bf2f(gtv[j]));
;                     }
.LBB0_186:
	v_lshl_add_u64 v[36:37], v[58:59], 1, s[36:37]
	v_mad_u64_u32 v[36:37], s[36:37], s14, v107, v[36:37]
	v_cvt_pk_bf16_f32 v40, v43, v43
	v_mov_b32_e32 v38, v37
	v_mad_u64_u32 v[38:39], s[14:15], s14, v69, v[38:39]
	v_mov_b32_e32 v37, v38
	v_lshl_add_u64 v[36:37], v[36:37], 0, s[2:3]
	s_and_b64 vcc, exec, s[10:11]
	v_or_b32_e32 v68, s38, v68
	global_store_short v[36:37], v40, off
	s_cbranch_vccnz .LBB0_188
	v_mad_u64_u32 v[36:37], s[2:3], v68, s77, v[66:67]
	v_mov_b32_e32 v38, v37
	v_mad_u64_u32 v[38:39], s[2:3], v69, s77, v[38:39]
	v_mov_b32_e32 v37, v38
	v_mad_u64_u32 v[38:39], s[2:3], v68, s43, v[64:65]
	v_mov_b32_e32 v40, v39
	v_lshl_add_u64 v[42:43], v[36:37], 0, s[50:51]
	global_load_ushort v77, v[36:37], off
	global_load_ushort v79, v[36:37], off offset:2560
	global_load_ushort v81, v[42:43], off offset:2560
	v_mad_u64_u32 v[40:41], s[2:3], v69, s43, v[40:41]
	v_add_co_u32_e32 v36, vcc, s33, v38
	v_mov_b32_e32 v39, v40
	s_nop 0
	v_addc_co_u32_e32 v37, vcc, 0, v40, vcc
	global_load_ushort v78, v[38:39], off
	global_load_ushort v80, v[36:37], off offset:1024
	v_lshl_add_u64 v[36:37], v[42:43], 0, s[50:51]
	v_add_co_u32_e32 v42, vcc, 0x2000, v38
	s_nop 1
	v_addc_co_u32_e32 v43, vcc, 0, v40, vcc
	global_load_ushort v85, v[42:43], off offset:2048
	global_load_ushort v84, v[36:37], off offset:2560
	v_add_co_u32_e32 v36, vcc, 0x3000, v38
	s_nop 1
	v_addc_co_u32_e32 v37, vcc, 0, v40, vcc
	global_load_ushort v91, v[36:37], off offset:3072

; __device__ __forceinline__ bf16_t f2bf(float f) { unsigned u = __float_as_uint(f); u += 0x7FFFu + ((u >> 16) & 1u); return (bf16_t)(u >> 16); }
; __device__ __forceinline__ float bf2f(bf16_t b) { return __uint_as_float(((unsigned)b) << 16); }
; __device__ void lru_fused_phase(const int bid, const int nblk, bf16_t* __restrict__ U, bf16_t* __restrict__ HF, const bf16_t* __restrict__ Wg, const float* __restrict__ cw, const float* __restrict__ cb, ...
;     ...
; #pragma unroll
;                     for (int j = 0; j < 4; ++j) {
;                         const float hv = hl[j] + pp[j] * carry;
;                         if (e == 0) HF[(grow + j) * DRNN + ch] = f2bf(hv);
;                         else U[(grow + j) * (2 * DRNN) + ch] = f2bf((bf2f(hfv[j]) + hv) * bf2f(gtv[j]));
;                     }
.LBB0_203:
	v_fmac_f32_e32 v36, v10, v37
	s_waitcnt vmcnt(7)
	v_lshlrev_b32_e32 v10, 16, v77
	v_add_f32_e32 v10, v36, v10
	s_waitcnt vmcnt(4) lgkmcnt(0)
	v_lshlrev_b32_e32 v38, 16, v78
	v_mul_f32_e32 v10, v10, v38
	v_cndmask_b32_e64 v10, v10, v36, s[60:61]
	v_lshl_add_u64 v[40:41], v[58:59], 1, s[14:15]
	v_mad_u64_u32 v[40:41], s[14:15], s10, v68, v[40:41]
	v_cvt_pk_bf16_f32 v36, v10, v10
	v_mov_b32_e32 v10, v41
	v_mad_u64_u32 v[110:111], s[14:15], s10, v69, v[10:11]
	v_mov_b32_e32 v41, v110
	v_fmac_f32_e32 v108, v107, v37
	v_lshlrev_b32_e32 v10, 16, v79
	global_store_short v[40:41], v36, off
	v_add_f32_e32 v10, v108, v10
	s_waitcnt vmcnt(4)
	v_lshlrev_b32_e32 v36, 16, v80
	v_mul_f32_e32 v10, v10, v36
	v_cndmask_b32_e64 v10, v10, v108, s[60:61]
	v_cvt_pk_bf16_f32 v10, v10, v10
	v_lshl_add_u64 v[40:41], v[40:41], 0, s[10:11]
	v_fmac_f32_e32 v43, v104, v37
	s_and_b64 vcc, exec, s[8:9]
	s_mov_b64 s[10:11], 0xa00
	global_store_short v[40:41], v10, off
	s_cbranch_vccnz .LBB0_205
	v_lshlrev_b32_e32 v10, 16, v81
	v_add_f32_e32 v10, v43, v10
	s_waitcnt vmcnt(4)
	v_lshlrev_b32_e32 v36, 16, v85
	v_mul_f32_e32 v43, v10, v36
	s_mov_b64 s[2:3], 0x2800
	s_mov_b64 s[14:15], 0x1400
	s_mov_b64 s[36:37], s[46:47]
	s_branch .LBB0_206

; __device__ __forceinline__ bf16_t f2bf(float f) { unsigned u = __float_as_uint(f); u += 0x7FFFu + ((u >> 16) & 1u); return (bf16_t)(u >> 16); }
; __device__ __forceinline__ float bf2f(bf16_t b) { return __uint_as_float(((unsigned)b) << 16); }
; __device__ void lru_fused_phase(const int bid, const int nblk, bf16_t* __restrict__ U, bf16_t* __restrict__ HF, const bf16_t* __restrict__ Wg, const float* __restrict__ cw, const float* __restrict__ cb, ...
;     ...
; #pragma unroll
;                     for (int j = 0; j < 4; ++j) {
;                         const float hv = hl[j] + pp[j] * carry;
;                         if (e == 0) HF[(grow + j) * DRNN + ch] = f2bf(hv);
;                         else U[(grow + j) * (2 * DRNN) + ch] = f2bf((bf2f(hfv[j]) + hv) * bf2f(gtv[j]));
;                     }
.LBB0_206:
	v_lshl_add_u64 v[40:41], v[58:59], 1, s[36:37]
	v_mad_u64_u32 v[40:41], s[36:37], s14, v68, v[40:41]
	v_cvt_pk_bf16_f32 v36, v43, v43
	v_mov_b32_e32 v10, v41
	v_mad_u64_u32 v[106:107], s[14:15], s14, v69, v[10:11]
	v_mov_b32_e32 v41, v106
	v_lshl_add_u64 v[40:41], v[40:41], 0, s[2:3]
	v_fmac_f32_e32 v42, v39, v37
	s_and_b64 vcc, exec, s[8:9]
	s_mov_b64 s[2:3], 0x1e00
	global_store_short v[40:41], v36, off
	s_cbranch_vccnz .LBB0_208
	s_waitcnt vmcnt(4)
	v_lshlrev_b32_e32 v10, 16, v84
	v_add_f32_e32 v10, v42, v10
	s_waitcnt vmcnt(3)
	v_lshlrev_b32_e32 v36, 16, v91
	v_mul_f32_e32 v42, v10, v36
	s_mov_b64 s[2:3], 0x3c00
	s_mov_b64 s[10:11], 0x1400
	s_mov_b64 s[8:9], s[46:47]
	s_branch .LBB0_209

; __device__ __forceinline__ unsigned cvt_pk_bf16(float lo, float hi) { unsigned r; asm volatile("v_cvt_pk_bf16_f32 %0, %1, %2" : "=v"(r) : "v"(lo), "v"(hi)); return r; }
; __device__ __forceinline__ bf16_t f2bf(float f) { unsigned u = __float_as_uint(f); u += 0x7FFFu + ((u >> 16) & 1u); return (bf16_t)(u >> 16); }
; __device__ __forceinline__ float bf2f(bf16_t b) { return __uint_as_float(((unsigned)b) << 16); }
; __device__ __forceinline__ float bflo(unsigned w) { return __uint_as_float(w << 16); }
; __device__ __forceinline__ float bfhi(unsigned w) { return __uint_as_float(w & 0xffff0000u); }
; __device__ void lru_fused_phase(const int bid, const int nblk, bf16_t* __restrict__ U, bf16_t* __restrict__ HF, const bf16_t* __restrict__ Wg, const float* __restrict__ cw, const float* __restrict__ cb, ...
;     ...
; #pragma unroll
;                     for (int j = 0; j < 4; ++j) {
;                         const float hv = hl[j] + pp[j] * carry;
;                         if (e == 0) HF[(grow + j) * DRNN + ch] = f2bf(hv);
;                         else U[(grow + j) * (2 * DRNN) + ch] = f2bf((bf2f(hfv[j]) + hv) * bf2f(gtv[j]));
;                     }
;     ...
;                 if (kk + 1 < 32) {
;                     unsigned char* nb = smem + ((kk + 1) & 1) * (64 * RS);
; #pragma unroll
;                     for (int r = 0; r < 8; ++r) {
;                         const float c0 = wb[0] + w0[0] * bflo(xr[r]) + w1[0] * bflo(xr[r + 1]) + w2[0] * bflo(xr[r + 2]) + w3[0] * bflo(xr[r + 3]);
;                         const float c1 = wb[1] + w0[1] * bfhi(xr[r]) + w1[1] * bfhi(xr[r + 1]) + w2[1] * bfhi(xr[r + 2]) + w3[1] * bfhi(xr[r + 3]);
;                         *(unsigned*)(nb + (8 * wid + r) * RS + lane * 4) = cvt_pk_bf16(c0, c1);
;                     }
.LBB0_209:
	v_lshl_add_u64 v[36:37], v[58:59], 1, s[8:9]
	v_mad_u64_u32 v[36:37], s[8:9], s10, v68, v[36:37]
	v_cvt_pk_bf16_f32 v40, v42, v42
	v_mov_b32_e32 v10, v37
	v_mad_u64_u32 v[38:39], s[8:9], s10, v69, v[10:11]
	v_mov_b32_e32 v37, v38
	v_lshl_add_u64 v[36:37], v[36:37], 0, s[2:3]
	s_andn2_b64 vcc, exec, s[52:53]
	global_store_short v[36:37], v40, off
	s_cbranch_vccnz .LBB0_92
	v_lshlrev_b32_e32 v10, 16, v87
	v_and_b32_e32 v39, 0xffff0000, v87
	v_fma_f32 v10, v48, v10, v56
	v_lshlrev_b32_e32 v36, 16, v88
	v_fma_f32 v39, v49, v39, v57
	v_and_b32_e32 v40, 0xffff0000, v88
	v_fmac_f32_e32 v10, v50, v36
	v_lshlrev_b32_e32 v37, 16, v89
	v_fmac_f32_e32 v39, v51, v40
	v_and_b32_e32 v41, 0xffff0000, v89
	s_bitcmp1_b32 s72, 0
	v_fmac_f32_e32 v10, v52, v37
	v_lshlrev_b32_e32 v38, 16, v90
	v_fmac_f32_e32 v39, v53, v41
	v_and_b32_e32 v42, 0xffff0000, v90
	s_cselect_b32 s2, 0x4400, 0
	v_fmac_f32_e32 v10, v54, v38
	v_fmac_f32_e32 v39, v55, v42
	v_cvt_pk_bf16_f32 v10, v10, v39
	v_add_u32_e32 v39, s2, v75
	ds_write_b32 v39, v10
	v_fma_f32 v10, v48, v36, v56
	v_fmac_f32_e32 v10, v50, v37
	v_fma_f32 v40, v49, v40, v57
	v_fmac_f32_e32 v10, v52, v38
	v_lshlrev_b32_e32 v36, 16, v92
	v_fmac_f32_e32 v40, v51, v41
	v_fmac_f32_e32 v10, v54, v36
	v_fmac_f32_e32 v40, v53, v42
	v_and_b32_e32 v43, 0xffff0000, v92
	v_fmac_f32_e32 v40, v55, v43
	v_cvt_pk_bf16_f32 v10, v10, v40
	ds_write_b32 v39, v10 offset:272
	v_fma_f32 v10, v48, v37, v56
	v_fmac_f32_e32 v10, v50, v38
	v_fma_f32 v40, v49, v41, v57
	v_fmac_f32_e32 v10, v52, v36
	v_lshlrev_b32_e32 v37, 16, v93
	v_fmac_f32_e32 v40, v51, v42
	v_fmac_f32_e32 v10, v54, v37
	v_fmac_f32_e32 v40, v53, v43
	v_and_b32_e32 v41, 0xffff0000, v93
	v_fmac_f32_e32 v40, v55, v41
	v_cvt_pk_bf16_f32 v10, v10, v40
	ds_write_b32 v39, v10 offset:544
	v_fma_f32 v10, v48, v38, v56
	v_fmac_f32_e32 v10, v50, v36
	v_fma_f32 v40, v49, v42, v57
	v_fmac_f32_e32 v10, v52, v37
	v_lshlrev_b32_e32 v38, 16, v94
	v_fmac_f32_e32 v40, v51, v43
	v_fmac_f32_e32 v10, v54, v38
	v_fmac_f32_e32 v40, v53, v41
	v_and_b32_e32 v42, 0xffff0000, v94
	v_fmac_f32_e32 v40, v55, v42
	v_cvt_pk_bf16_f32 v10, v10, v40
	ds_write_b32 v39, v10 offset:816
	v_fma_f32 v10, v48, v36, v56
	v_fmac_f32_e32 v10, v50, v37
	v_fma_f32 v40, v49, v43, v57
	v_fmac_f32_e32 v10, v52, v38
	v_lshlrev_b32_e32 v36, 16, v95
	v_fmac_f32_e32 v40, v51, v41
	v_fmac_f32_e32 v10, v54, v36
	v_fmac_f32_e32 v40, v53, v42
	v_and_b32_e32 v43, 0xffff0000, v95
	v_fmac_f32_e32 v40, v55, v43
	v_cvt_pk_bf16_f32 v10, v10, v40
	ds_write_b32 v39, v10 offset:1088
	v_fma_f32 v10, v48, v37, v56
	v_fmac_f32_e32 v10, v50, v38
	v_fma_f32 v40, v49, v41, v57
	v_fmac_f32_e32 v10, v52, v36
	v_lshlrev_b32_e32 v37, 16, v96
	v_fmac_f32_e32 v40, v51, v42
	v_fmac_f32_e32 v10, v54, v37
	v_fmac_f32_e32 v40, v53, v43
	v_and_b32_e32 v41, 0xffff0000, v96
	v_fmac_f32_e32 v40, v55, v41
	v_cvt_pk_bf16_f32 v10, v10, v40
	ds_write_b32 v39, v10 offset:1360
	v_fma_f32 v10, v48, v38, v56
	v_fmac_f32_e32 v10, v50, v36
	v_fma_f32 v40, v49, v42, v57
	v_fmac_f32_e32 v10, v52, v37
	v_lshlrev_b32_e32 v38, 16, v97
	v_fmac_f32_e32 v40, v51, v43
	v_fmac_f32_e32 v10, v54, v38
	v_fmac_f32_e32 v40, v53, v41
	v_and_b32_e32 v42, 0xffff0000, v97
	v_fmac_f32_e32 v40, v55, v42
	v_cvt_pk_bf16_f32 v10, v10, v40
	ds_write_b32 v39, v10 offset:1632
	v_fma_f32 v10, v48, v36, v56
	v_fmac_f32_e32 v10, v50, v37
	v_fmac_f32_e32 v10, v52, v38
	v_lshlrev_b32_e32 v36, 16, v103
	v_fmac_f32_e32 v10, v54, v36
	v_fma_f32 v36, v49, v43, v57
	v_fmac_f32_e32 v36, v51, v41
	v_fmac_f32_e32 v36, v53, v42
	v_and_b32_e32 v37, 0xffff0000, v103
	v_fmac_f32_e32 v36, v55, v37
	v_cvt_pk_bf16_f32 v10, v10, v36
	ds_write_b32 v39, v10 offset:1904
	s_branch .LBB0_92
